# mode-B loop: bias LDS reads issued under the QK MFMAs (counted lgkmcnt), second V batch reads issued ahead of the first PV MFMAs
# speedup vs baseline: 1.0125x; 1.0030x over previous
; __device__ __forceinline__ unsigned pk2(float lo, float hi) { f32x2 v = {lo, hi}; bf16x2_t b = __builtin_convertvector(v, bf16x2_t); return __builtin_bit_cast(unsigned, b); }
; __device__ __forceinline__ float fast_exp2(float x) { return __builtin_amdgcn_exp2f(x); }
; #define MFMA32(a, b, c) __builtin_amdgcn_mfma_f32_32x32x16_bf16((a), (b), (c), 0, 0, 0)
; #define LGKM0() asm volatile("s_waitcnt lgkmcnt(0)" ::: "memory")
; #define SBAR() __builtin_amdgcn_sched_barrier(0)
; #define V_ISSUE(va, b, d) do { _Pragma("unroll") for (int k4 = 0; k4 < 4; ++k4) { DS_TR16(vlo[b][k4], va, (16 * k4) * VP + (d) * 64); DS_TR16(vhi[b][k4], va, (16 * k4 + 8) * VP + (d) * 64); } } while (0)
; template <int DQK, int DV, int MODE>
; __device__ __forceinline__ void attn_item(LAS unsigned char* lds, int item, const AttnCtx& cx) {
;     ...
;         for (int i = 0; i < 16; ++i) { s0[i] = fast_exp2(s0[i]); s1[i] = fast_exp2(s1[i]); }
;         u32x4 w;
;         w.x = pk2(s0[0], s0[1]); w.y = pk2(s0[2], s0[3]); w.z = pk2(s0[4], s0[5]); w.w = pk2(s0[6], s0[7]); pa[0][0] = __builtin_bit_cast(bf16x8, w);
;         w.x = pk2(s0[8], s0[9]); w.y = pk2(s0[10], s0[11]); w.z = pk2(s0[12], s0[13]); w.w = pk2(s0[14], s0[15]); pa[0][1] = __builtin_bit_cast(bf16x8, w);
;         w.x = pk2(s1[0], s1[1]); w.y = pk2(s1[2], s1[3]); w.z = pk2(s1[4], s1[5]); w.w = pk2(s1[6], s1[7]); pa[1][0] = __builtin_bit_cast(bf16x8, w);
;         w.x = pk2(s1[8], s1[9]); w.y = pk2(s1[10], s1[11]); w.z = pk2(s1[12], s1[13]); w.w = pk2(s1[14], s1[15]); pa[1][1] = __builtin_bit_cast(bf16x8, w);
;     };
;     auto do_pv = [&](unsigned va) {
; #pragma unroll
;         for (int k4 = 0; k4 < 4; ++k4) Lacc = MFMA32(ones8, pa[k4 >> 1][k4 & 1], Lacc);
; #pragma unroll
;         for (int d = 0; d < NDV; ++d) {
;             LGKM0(); SBAR();
; #pragma unroll
;             for (int k4 = 0; k4 < 4; ++k4) {
;                 const bf16x8 vf = __builtin_shufflevector(vlo[d & 1][k4], vhi[d & 1][k4], 0, 1, 2, 3, 4, 5, 6, 7);
;                 O[d] = MFMA32(vf, pa[k4 >> 1][k4 & 1], O[d]);
;             }
;             SBAR();
;             if (d + 1 < NDV) V_ISSUE(va, (d + 1) & 1, d + 1);
;         }
.LBB0_330:
	v_exp_f32_e32 v130, v130
	v_exp_f32_e32 v131, v131
	v_exp_f32_e32 v132, v132
	v_exp_f32_e32 v133, v133
	s_mov_b32 s90, s88
	s_mov_b32 s91, s88
	v_exp_f32_e32 v211, v118
	v_exp_f32_e32 v118, v135
	v_exp_f32_e32 v135, v119
	v_exp_f32_e32 v119, v136
	v_exp_f32_e32 v136, v120
	v_exp_f32_e32 v120, v137
	v_exp_f32_e32 v137, v138
	v_exp_f32_e32 v138, v122
	v_exp_f32_e32 v122, v139
	v_exp_f32_e32 v139, v123
	v_exp_f32_e32 v123, v140
	v_exp_f32_e32 v140, v124
	v_exp_f32_e32 v124, v141
	v_exp_f32_e32 v141, v125
	v_exp_f32_e32 v125, v142
	v_exp_f32_e32 v142, v126
	v_exp_f32_e32 v212, v127
	v_cvt_pk_bf16_f32 v126, v130, v131
	v_cvt_pk_bf16_f32 v127, v132, v133
	s_mov_b32 s89, s88
	v_mov_b64_e32 v[132:133], s[90:91]
	v_exp_f32_e32 v134, v134
	v_mov_b64_e32 v[130:131], s[88:89]
	v_exp_f32_e32 v213, v128
	v_exp_f32_e32 v214, v129
	v_cvt_pk_bf16_f32 v128, v134, v118
	v_cvt_pk_bf16_f32 v129, v119, v120
	v_exp_f32_e32 v143, v143
	v_exp_f32_e32 v144, v144
	v_mfma_f32_32x32x16_bf16 v[34:49], v[130:133], v[126:129], v[34:49]
	v_exp_f32_e32 v145, v145
	v_cvt_pk_bf16_f32 v122, v137, v122
	v_cvt_pk_bf16_f32 v123, v123, v124
	v_cvt_pk_bf16_f32 v124, v125, v143
	v_cvt_pk_bf16_f32 v125, v144, v145
	v_exp_f32_e32 v114, v114
	v_exp_f32_e32 v115, v115
	v_mfma_f32_32x32x16_bf16 v[34:49], v[130:133], v[122:125], v[34:49]
	v_exp_f32_e32 v116, v116
	v_exp_f32_e32 v117, v117
	v_exp_f32_e32 v121, v121
	v_cvt_pk_bf16_f32 v118, v114, v115
	v_cvt_pk_bf16_f32 v120, v211, v135
	v_cvt_pk_bf16_f32 v119, v116, v117
	v_cvt_pk_bf16_f32 v121, v136, v121
	v_cvt_pk_bf16_f32 v114, v138, v139
	v_cvt_pk_bf16_f32 v115, v140, v141
	v_mfma_f32_32x32x16_bf16 v[34:49], v[130:133], v[118:121], v[34:49]
	v_cvt_pk_bf16_f32 v116, v142, v212
	v_cvt_pk_bf16_f32 v117, v213, v214
	s_waitcnt lgkmcnt(0)
	s_nop 1
	v_mfma_f32_32x32x16_bf16 v[34:49], v[130:133], v[114:117], v[34:49]
	ds_read_b64_tr_b16 v[130:131], v210 offset:64
	ds_read_b64_tr_b16 v[132:133], v210 offset:1600
	ds_read_b64_tr_b16 v[134:135], v210 offset:3136
	ds_read_b64_tr_b16 v[136:137], v210 offset:4672
	ds_read_b64_tr_b16 v[138:139], v210 offset:6208
	ds_read_b64_tr_b16 v[140:141], v210 offset:7744
	ds_read_b64_tr_b16 v[142:143], v210 offset:9280
	ds_read_b64_tr_b16 v[144:145], v210 offset:10816
	v_mfma_f32_32x32x16_bf16 v[18:33], v[190:193], v[126:129], v[18:33]
	v_mfma_f32_32x32x16_bf16 v[18:33], v[186:189], v[122:125], v[18:33]
	v_mfma_f32_32x32x16_bf16 v[18:33], v[182:185], v[118:121], v[18:33]
	v_mfma_f32_32x32x16_bf16 v[18:33], v[178:181], v[114:117], v[18:33]
	s_waitcnt lgkmcnt(0)
	s_nop 0
	v_mfma_f32_32x32x16_bf16 v[2:17], v[130:133], v[126:129], v[2:17]
	v_mfma_f32_32x32x16_bf16 v[2:17], v[134:137], v[122:125], v[2:17]
	v_mfma_f32_32x32x16_bf16 v[2:17], v[138:141], v[118:121], v[2:17]
	v_mfma_f32_32x32x16_bf16 v[2:17], v[142:145], v[114:117], v[2:17]
	s_mov_b64 s[38:39], 0

; __device__ __forceinline__ int crow(int i, int h) { return (i & 3) + 8 * (i >> 2) + 4 * h; }
; template <int DQK, int DV, int MODE>
; __device__ __forceinline__ void attn_item(LAS unsigned char* lds, int item, const AttnCtx& cx) {
;     ...
;     auto do_qk = [&](int j, bool vpre) {
;         const unsigned kaddr = (unsigned)(size_t)(lds + (j % NST) * SB + koff) + r * KP + 16 * h;
;         const unsigned va = vaddr_of(j);
;         bf16x8 kfr[1][4];
;         K_ISSUE(0, 0);
; #pragma unroll
;         for (int kb = 0; kb < NQF / 2; ++kb) {
;             LGKM0(); SBAR();
;             if (kb == 0) { if (MODE == 1) { s0 = MFMA32(kfr[0][0], qf[0], cin0); s1 = MFMA32(kfr[0][1], qf[0], cin1); } else { s0 = MFMA32(kfr[0][0], qf[0], negm); s1 = MFMA32(kfr[0][1], qf[0], negm); } }
;             else { s0 = MFMA32(kfr[0][0], qf[2 * kb], s0); s1 = MFMA32(kfr[0][1], qf[2 * kb], s1); }
;             s0 = MFMA32(kfr[0][2], qf[2 * kb + 1], s0); s1 = MFMA32(kfr[0][3], qf[2 * kb + 1], s1);
;             SBAR();
;             if (kb + 1 < NQF / 2) K_ISSUE(0, kb + 1); else if (vpre) V_ISSUE(va, 0, 0);
;         }
;     };
;     auto do_soft = [&](int j) {
;         if (MODE == 1) {
;             const int rk = na_rs0 + j; const int bbase = (rk - na_rq + 7) * 31 + 15 - na_cq + 64;
; #pragma unroll
;             for (int i = 0; i < 16; ++i) { s0[i] += biasL[bbase + crow(i, h)]; s1[i] += biasL[bbase + crow(i, h) + 32]; }
;         }
;         if (MODE == 2) {
;             const int lk0 = c_l0 - 64 + 64 * j;
; #pragma unroll
;             for (int i = 0; i < 16; ++i) {
;                 const int lka = lk0 + crow(i, h), lkb = lka + 32;
;                 const bool v0 = (lka >= 0) && (lka < c_L) && (abs(lka - c_lq) <= 64), v1 = (lkb >= 0) && (lkb < c_L) && (abs(lkb - c_lq) <= 64);
;                 s0[i] = v0 ? s0[i] : NEGBIG; s1[i] = v1 ? s1[i] : NEGBIG;
;             }
;         }
;         float mx = max3f(s0[0], s1[0], s0[1]);
;         mx = max3f(mx, s1[1], s0[2]);
; #pragma unroll
;         for (int i = 2; i < 15; ++i) mx = max3f(mx, s1[i], s0[i + 1]);
;         mx = fmaxf(mx, s1[15]);
;         { auto rr = __builtin_amdgcn_permlane32_swap(__float_as_uint(mx), __float_as_uint(mx), false, false); mx = max3f(__uint_as_float(rr[0]), __uint_as_float(rr[1]), __uint_as_float(rr[0])); }
;         if (first || __builtin_amdgcn_ballot_w64(mx > THR) != 0ull) {
.LBB0_332:
	s_add_i32 s40, s51, s22
	s_add_i32 s0, s40, 1
	s_min_i32 s0, s0, s36
	s_lshl_b32 s41, s0, 6
	v_add_u32_e32 v116, s41, v199
	v_mov_b64_e32 v[114:115], s[86:87]
	v_mad_i64_i32 v[116:117], s[0:1], v116, s33, v[114:115]
	v_add_u32_e32 v120, s41, v200
	v_lshl_add_u64 v[118:119], v[116:117], 0, s[96:97]
	v_mad_i64_i32 v[114:115], s[0:1], v120, s33, v[114:115]
	v_lshl_add_u64 v[116:117], v[116:117], 0, s[94:95]
	v_lshl_add_u64 v[118:119], v[118:119], 0, v[0:1]
	v_lshl_add_u64 v[120:121], v[114:115], 0, s[96:97]
	v_lshl_add_u64 v[116:117], v[116:117], 0, v[0:1]
	v_lshl_add_u64 v[114:115], v[114:115], 0, s[94:95]
	v_lshl_add_u64 v[120:121], v[120:121], 0, v[0:1]
	global_load_dwordx4 v[162:165], v[118:119], off
	global_load_dwordx4 v[166:169], v[120:121], off
	v_lshl_add_u64 v[114:115], v[114:115], 0, v[0:1]
	global_load_dwordx4 v[170:173], v[116:117], off
	global_load_dwordx4 v[174:177], v[114:115], off
	s_cmp_ge_u32 s40, s37
	s_cselect_b64 s[0:1], -1, 0
	s_cmp_lt_u32 s40, s42
	s_cselect_b64 s[40:41], -1, 0
	s_and_b64 s[0:1], s[0:1], s[40:41]
	s_andn2_b64 vcc, exec, s[0:1]
	s_cbranch_vccnz .LBB0_331
	s_xor_b64 s[40:41], s[38:39], -1
	s_bitcmp1_b32 s22, 0
	s_cselect_b32 s0, 0xa800, 0
	s_add_i32 s0, s23, s0
	v_add_u32_e32 v211, s0, v204
	ds_read_b128 v[114:117], v211 offset:0
	ds_read_b128 v[178:181], v211 offset:4608
	ds_read_b128 v[182:185], v211 offset:32
	ds_read_b128 v[186:189], v211 offset:4640
	s_waitcnt lgkmcnt(0)
	s_addk_i32 s0, 0x2400
	v_add_u32_e32 v210, s0, v207
	v_mfma_f32_32x32x16_bf16 v[130:145], v[114:117], v[158:161], v[98:113]
	v_mfma_f32_32x32x16_bf16 v[114:129], v[178:181], v[158:161], v[82:97]
	v_mfma_f32_32x32x16_bf16 v[130:145], v[182:185], v[154:157], v[130:145]
	v_mfma_f32_32x32x16_bf16 v[114:129], v[186:189], v[154:157], v[114:129]
	ds_read_b128 v[178:181], v211 offset:64
	ds_read_b128 v[182:185], v211 offset:4672
	ds_read_b128 v[186:189], v211 offset:96
	ds_read_b128 v[190:193], v211 offset:4704
	v_add_u32_e32 v214, s43, v208
	v_add_u32_e32 v214, 0x15880, v214
	ds_read2_b32 v[222:223], v214 offset0:0 offset1:1
	ds_read2_b32 v[224:225], v214 offset0:32 offset1:33
	ds_read2_b32 v[226:227], v214 offset0:2 offset1:3
	ds_read2_b32 v[228:229], v214 offset0:34 offset1:35
	ds_read2_b32 v[230:231], v214 offset0:8 offset1:9
	ds_read2_b32 v[232:233], v214 offset0:40 offset1:41
	ds_read2_b32 v[234:235], v214 offset0:10 offset1:11
	ds_read2_b32 v[236:237], v214 offset0:42 offset1:43
	ds_read2_b32 v[238:239], v214 offset0:16 offset1:17
	ds_read2_b32 v[240:241], v214 offset0:48 offset1:49
	ds_read2_b32 v[242:243], v214 offset0:18 offset1:19
	ds_read2_b32 v[244:245], v214 offset0:50 offset1:51
	s_waitcnt lgkmcnt(12)
	s_nop 0
	v_mfma_f32_32x32x16_bf16 v[130:145], v[178:181], v[150:153], v[130:145]
	v_mfma_f32_32x32x16_bf16 v[114:129], v[182:185], v[150:153], v[114:129]
	v_mfma_f32_32x32x16_bf16 v[130:145], v[186:189], v[146:149], v[130:145]
	v_mfma_f32_32x32x16_bf16 v[114:129], v[190:193], v[146:149], v[114:129]
	ds_read_b64_tr_b16 v[190:191], v210 offset:0
	ds_read_b64_tr_b16 v[192:193], v210 offset:1536
	ds_read_b64_tr_b16 v[186:187], v210 offset:3072
	ds_read_b64_tr_b16 v[188:189], v210 offset:4608
	ds_read_b64_tr_b16 v[182:183], v210 offset:6144
	ds_read_b64_tr_b16 v[184:185], v210 offset:7680
	ds_read_b64_tr_b16 v[178:179], v210 offset:9216
	ds_read_b64_tr_b16 v[180:181], v210 offset:10752
	ds_read2_b32 v[246:247], v214 offset0:24 offset1:25
	ds_read2_b32 v[248:249], v214 offset0:56 offset1:57
	ds_read2_b32 v[212:213], v214 offset0:26 offset1:27
	ds_read2_b32 v[216:217], v214 offset0:58 offset1:59
	s_andn2_b64 vcc, exec, s[40:41]
	s_waitcnt lgkmcnt(0)
	s_nop 4
	v_pk_add_f32 v[130:131], v[130:131], v[222:223]
	v_pk_add_f32 v[114:115], v[114:115], v[224:225]
	v_pk_add_f32 v[132:133], v[132:133], v[226:227]
	v_pk_add_f32 v[116:117], v[116:117], v[228:229]
	v_pk_add_f32 v[134:135], v[134:135], v[230:231]
	v_pk_add_f32 v[118:119], v[118:119], v[232:233]
	v_pk_add_f32 v[136:137], v[136:137], v[234:235]
	v_pk_add_f32 v[120:121], v[120:121], v[236:237]
	v_pk_add_f32 v[138:139], v[138:139], v[238:239]
	v_pk_add_f32 v[122:123], v[122:123], v[240:241]
	v_pk_add_f32 v[140:141], v[140:141], v[242:243]
	v_pk_add_f32 v[124:125], v[124:125], v[244:245]
	v_pk_add_f32 v[142:143], v[142:143], v[246:247]
	v_pk_add_f32 v[126:127], v[126:127], v[248:249]
	v_pk_add_f32 v[144:145], v[144:145], v[212:213]
	v_pk_add_f32 v[128:129], v[128:129], v[216:217]
	v_max3_f32 v211, v130, v114, v131
	v_max3_f32 v211, v211, v115, v132
	s_nop 0
	v_max3_f32 v211, v211, v116, v133
	s_nop 0
	v_max3_f32 v211, v211, v117, v134
	s_nop 0
	v_max3_f32 v211, v211, v118, v135
	s_nop 0
	v_max3_f32 v211, v211, v119, v136
	s_nop 0
	v_max3_f32 v211, v211, v120, v137
	s_nop 0
	v_max3_f32 v211, v211, v121, v138
	s_nop 0
	v_max3_f32 v211, v211, v122, v139
	s_nop 0
	v_max3_f32 v211, v211, v123, v140
	s_nop 0
	v_max3_f32 v211, v211, v124, v141
	s_nop 0
	v_max3_f32 v211, v211, v125, v142
	s_nop 0
	v_max3_f32 v211, v211, v126, v143
	s_nop 0
	v_max3_f32 v211, v211, v127, v144
	s_nop 0
	v_max3_f32 v211, v211, v128, v145
	s_nop 0
	v_max_f32_e32 v211, v211, v211
	v_max_f32_e32 v211, v211, v129
	v_mov_b32_e32 v212, v211
	s_nop 1
	v_permlane32_swap_b32_e32 v211, v212
	v_max3_f32 v211, v211, v212, v211
	v_cndmask_b32_e64 v212, 0, 1, s[40:41]
	v_cmp_ne_u32_e64 s[0:1], 1, v212
	s_mov_b64 s[40:41], s[38:39]
	s_cbranch_vccnz .LBB0_335
	v_cmp_lt_f32_e32 vcc, s29, v211
	s_cmp_lg_u64 vcc, 0
	s_cselect_b64 s[40:41], -1, 0
